# PROJ GEMM: compact fast epilogue for non-gelu non-dt tiles (cached row scales, no per-element branches)
# speedup vs baseline: 1.0198x; 1.0083x over previous
.LBB0_799:
	v_readlane_b32 s10, v254, 20
	v_readlane_b32 s11, v254, 21
	s_and_b64 s[10:11], s[10:11], exec
	v_readlane_b32 s10, v254, 35
	s_movk_i32 s7, 0x1300
	v_readlane_b32 s11, v254, 36
	s_cselect_b32 s41, s7, 0xe00
	s_cselect_b32 s7, 0, 0x800
	s_cselect_b32 s42, 0xf0f, 0
	s_cselect_b32 s17, s11, 0
	s_cselect_b32 s16, s10, 0
	s_cselect_b32 s43, 18, -1
	s_and_b32 s18, s0, 3
	s_add_i32 m0, s37, 0x18000
	v_lshl_add_u64 v[8:9], v[8:9], 0, s[86:87]
	s_lshl_b32 s0, s1, 13
	s_lshl_b32 s12, s18, 12
	global_load_lds_dwordx4 v[8:9], off
	v_lshl_add_u64 v[6:7], v[6:7], 0, s[86:87]
	s_add_i32 m0, s37, 0x1a000
	s_add_i32 s44, s37, 0x8000
	s_add_i32 s45, s37, 0xa000
	global_load_lds_dwordx4 v[6:7], off
	v_lshl_add_u64 v[2:3], v[2:3], 0, s[86:87]
	s_mov_b32 m0, s44
	s_add_u32 s10, s28, 0x40080
	global_load_lds_dwordx4 v[2:3], off
	v_lshl_add_u64 v[2:3], v[4:5], 0, s[86:87]
	s_mov_b32 m0, s45
	s_addc_u32 s11, s29, 0
	global_load_lds_dwordx4 v[2:3], off
	s_add_i32 m0, s37, 0x1c000
	v_lshl_add_u64 v[2:3], s[10:11], 0, v[0:1]
	global_load_lds_dwordx4 v[2:3], off
	v_lshl_add_u64 v[2:3], s[10:11], 0, v[158:159]
	s_add_i32 m0, s37, 0x1e000
	v_lshlrev_b32_e32 v4, 2, v221
	global_load_lds_dwordx4 v[2:3], off
	s_waitcnt vmcnt(8)
	s_barrier
	v_lshlrev_b32_e32 v2, 4, v220
	s_cmpk_lt_u32 s5, 0x100
	v_readlane_b32 s14, v254, 10
	v_lshl_or_b32 v3, v221, 6, v2
	v_and_b32_e32 v4, 32, v4
	s_cselect_b64 s[10:11], -1, 0
	s_cmp_eq_u32 s18, 0
	v_readlane_b32 s15, v254, 11
	v_bitop3_b32 v224, s12, v3, v4 bitop3:0xf6
	s_cselect_b64 s[12:13], -1, 0
	s_ashr_i32 s47, s14, 31
	v_readlane_b32 s14, v254, 32
	v_readlane_b32 s15, v254, 33
	s_add_u32 s14, s14, s7
	s_addc_u32 s15, s15, 0
	s_lshl_b32 s51, s4, 3
	v_bitop3_b32 v7, v3, s0, v4 bitop3:0xde
	v_lshlrev_b32_e32 v4, 5, v220
	v_mov_b32_e32 v5, v1
	v_cvt_f32_ubyte0_e32 v3, s51
	v_lshl_add_u64 v[160:161], s[16:17], 0, v[4:5]
	v_rcp_iflag_f32_e32 v4, v3
	v_readlane_b32 s4, v254, 30
	v_mov_b32_e32 v3, v1
	v_readlane_b32 s5, v254, 31
	v_mul_f32_e32 v4, 0x4f7ffffe, v4
	v_cvt_u32_f32_e32 v4, v4
	v_lshl_add_u64 v[170:171], s[4:5], 0, v[2:3]
	v_lshlrev_b32_e32 v2, 14, v10
	v_and_b32_e32 v2, 0xffff8000, v2
	s_lshr_b32 s48, s92, 3
	v_lshl_add_u32 v2, v11, 11, v2
	v_and_b32_e32 v3, 1, v10
	s_and_b32 s49, s92, 6
	s_add_i32 s50, s48, 1
	v_lshl_or_b32 v2, v3, 6, v2
	s_cmp_lg_u64 s[16:17], 0
	v_lshl_add_u32 v172, v12, 1, v2
	v_lshlrev_b32_e32 v2, 14, v13
	s_cselect_b64 s[16:17], -1, 0
	s_sub_i32 s4, 0, s51
	v_readfirstlane_b32 s5, v4
	v_and_b32_e32 v2, 0xffff8000, v2
	s_waitcnt vmcnt(6)
	s_mul_i32 s4, s4, s5
	v_lshl_add_u32 v2, v14, 11, v2
	v_and_b32_e32 v3, 1, v13
	v_lshlrev_b32_e32 v6, 3, v220
	s_mul_hi_u32 s4, s5, s4
	v_lshl_or_b32 v2, v3, 6, v2
	s_mov_b32 s101, -1
	s_mov_b32 s46, 0
	v_lshl_or_b32 v223, s1, 6, v221
	v_cmp_gt_u32_e64 s[0:1], 2, v220
	v_lshl_or_b32 v225, s18, 5, v6
	s_add_i32 s52, s5, s4
	v_mov_b32_e32 v173, v1
	v_lshl_add_u32 v174, v15, 1, v2
	v_mov_b32_e32 v175, v1
	v_add_u32_e32 v226, 0, v7
	s_barrier
	s_branch .LBB0_802

.LBB0_812:
	s_lshl_b32 s100, 1, s26
	s_and_b32 s100, s100, s42
	s_cmp_lg_u32 s100, 0
	s_cbranch_scc1 .Lpj_slow
	s_cmp_eq_u32 s26, s43
	s_cbranch_scc1 .Lpj_slow
	v_lshl_add_u32 v176, s6, 8, v223
	v_or_b32_e32 v177, 16, v176
	v_or_b32_e32 v178, 32, v176
	v_or_b32_e32 v179, 48, v176
	v_add_u32_e32 v180, 0x80, v176
	v_add_u32_e32 v181, 0x90, v176
	v_add_u32_e32 v182, 0xa0, v176
	v_add_u32_e32 v183, 0xb0, v176
	v_lshl_or_b32 v214, s26, 8, v225
	v_ashrrev_i32_e32 v215, 31, v214
	v_lshlrev_b64 v[214:215], 1, v[214:215]
	v_lshl_add_u64 v[214:215], s[14:15], 0, v[214:215]
	s_cmp_eq_u32 s101, s6
	s_cbranch_scc1 .Lpj_rs_cached
	v_mov_b32_e32 v152, v176
	v_ashrrev_i32_e32 v153, 31, v176
	v_lshlrev_b64 v[152:153], 6, v[152:153]
	v_lshl_add_u64 v[152:153], v[170:171], 0, v[152:153]
	global_load_dwordx4 v[184:187], v[152:153], off
	v_mov_b32_e32 v152, v177
	v_ashrrev_i32_e32 v153, 31, v177
	v_lshlrev_b64 v[152:153], 6, v[152:153]
	v_lshl_add_u64 v[152:153], v[170:171], 0, v[152:153]
	global_load_dwordx4 v[188:191], v[152:153], off
	v_mov_b32_e32 v152, v178
	v_ashrrev_i32_e32 v153, 31, v178
	v_lshlrev_b64 v[152:153], 6, v[152:153]
	v_lshl_add_u64 v[152:153], v[170:171], 0, v[152:153]
	global_load_dwordx4 v[192:195], v[152:153], off
	v_mov_b32_e32 v152, v179
	v_ashrrev_i32_e32 v153, 31, v179
	v_lshlrev_b64 v[152:153], 6, v[152:153]
	v_lshl_add_u64 v[152:153], v[170:171], 0, v[152:153]
	global_load_dwordx4 v[196:199], v[152:153], off
	v_mov_b32_e32 v152, v180
	v_ashrrev_i32_e32 v153, 31, v180
	v_lshlrev_b64 v[152:153], 6, v[152:153]
	v_lshl_add_u64 v[152:153], v[170:171], 0, v[152:153]
	global_load_dwordx4 v[200:203], v[152:153], off
	v_mov_b32_e32 v152, v181
	v_ashrrev_i32_e32 v153, 31, v181
	v_lshlrev_b64 v[152:153], 6, v[152:153]
	v_lshl_add_u64 v[152:153], v[170:171], 0, v[152:153]
	global_load_dwordx4 v[204:207], v[152:153], off
	v_mov_b32_e32 v152, v182
	v_ashrrev_i32_e32 v153, 31, v182
	v_lshlrev_b64 v[152:153], 6, v[152:153]
	v_lshl_add_u64 v[152:153], v[170:171], 0, v[152:153]
	global_load_dwordx4 v[228:231], v[152:153], off
	v_mov_b32_e32 v152, v183
	v_ashrrev_i32_e32 v153, 31, v183
	v_lshlrev_b64 v[152:153], 6, v[152:153]
	v_lshl_add_u64 v[152:153], v[170:171], 0, v[152:153]
	global_load_dwordx4 v[232:235], v[152:153], off
	v_xor_b32_e32 v146, 16, v211
	v_lshlrev_b32_e32 v146, 2, v146
	v_xor_b32_e32 v147, 32, v211
	v_lshlrev_b32_e32 v147, 2, v147
	s_waitcnt vmcnt(0)
	v_add_f32_e32 v152, v184, v185
	v_add_f32_e32 v153, v186, v187
	v_add_f32_e32 v130, v152, v153
	v_add_f32_e32 v152, v188, v189
	v_add_f32_e32 v153, v190, v191
	v_add_f32_e32 v132, v152, v153
	v_add_f32_e32 v152, v192, v193
	v_add_f32_e32 v153, v194, v195
	v_add_f32_e32 v134, v152, v153
	v_add_f32_e32 v152, v196, v197
	v_add_f32_e32 v153, v198, v199
	v_add_f32_e32 v136, v152, v153
	v_add_f32_e32 v152, v200, v201
	v_add_f32_e32 v153, v202, v203
	v_add_f32_e32 v138, v152, v153
	v_add_f32_e32 v152, v204, v205
	v_add_f32_e32 v153, v206, v207
	v_add_f32_e32 v140, v152, v153
	v_add_f32_e32 v152, v228, v229
	v_add_f32_e32 v153, v230, v231
	v_add_f32_e32 v142, v152, v153
	v_add_f32_e32 v152, v232, v233
	v_add_f32_e32 v153, v234, v235
	v_add_f32_e32 v144, v152, v153
	ds_bpermute_b32 v184, v146, v130
	ds_bpermute_b32 v188, v146, v132
	ds_bpermute_b32 v192, v146, v134
	ds_bpermute_b32 v196, v146, v136
	ds_bpermute_b32 v200, v146, v138
	ds_bpermute_b32 v204, v146, v140
	ds_bpermute_b32 v228, v146, v142
	ds_bpermute_b32 v232, v146, v144
	s_waitcnt lgkmcnt(0)
	v_add_f32_e32 v130, v130, v184
	v_add_f32_e32 v132, v132, v188
	v_add_f32_e32 v134, v134, v192
	v_add_f32_e32 v136, v136, v196
	v_add_f32_e32 v138, v138, v200
	v_add_f32_e32 v140, v140, v204
	v_add_f32_e32 v142, v142, v228
	v_add_f32_e32 v144, v144, v232
	ds_bpermute_b32 v184, v147, v130
	ds_bpermute_b32 v188, v147, v132
	ds_bpermute_b32 v192, v147, v134
	ds_bpermute_b32 v196, v147, v136
	ds_bpermute_b32 v200, v147, v138
	ds_bpermute_b32 v204, v147, v140
	ds_bpermute_b32 v228, v147, v142
	ds_bpermute_b32 v232, v147, v144
	s_waitcnt lgkmcnt(0)
	v_add_f32_e32 v130, v130, v184
	v_add_f32_e32 v132, v132, v188
	v_add_f32_e32 v134, v134, v192
	v_add_f32_e32 v136, v136, v196
	v_add_f32_e32 v138, v138, v200
	v_add_f32_e32 v140, v140, v204
	v_add_f32_e32 v142, v142, v228
	v_add_f32_e32 v144, v144, v232
	s_mov_b32 s100, 0x3a800000
	v_fma_f32 v130, v130, s100, v240
	v_fma_f32 v132, v132, s100, v240
	v_fma_f32 v134, v134, s100, v240
	v_fma_f32 v136, v136, s100, v240
	v_fma_f32 v138, v138, s100, v240
	v_fma_f32 v140, v140, s100, v240
	v_fma_f32 v142, v142, s100, v240
	v_fma_f32 v144, v144, s100, v240
	v_rsq_f32_e32 v130, v130
	v_rsq_f32_e32 v132, v132
	v_rsq_f32_e32 v134, v134
	v_rsq_f32_e32 v136, v136
	v_rsq_f32_e32 v138, v138
	v_rsq_f32_e32 v140, v140
	v_rsq_f32_e32 v142, v142
	v_rsq_f32_e32 v144, v144
	s_nop 0
	v_mov_b32_e32 v250, v130
	v_mov_b32_e32 v168, v132
	v_mov_b32_e32 v169, v134
	v_mov_b32_e32 v227, v136
	v_mov_b32_e32 v238, v138
	v_mov_b32_e32 v239, v140
	v_mov_b32_e32 v248, v142
	v_mov_b32_e32 v249, v144
	s_mov_b32 s101, s6
	s_branch .Lpj_rs_done
.Lpj_rs_cached:
	v_mov_b32_e32 v130, v250
	v_mov_b32_e32 v132, v168
	v_mov_b32_e32 v134, v169
	v_mov_b32_e32 v136, v227
	v_mov_b32_e32 v138, v238
	v_mov_b32_e32 v140, v239
	v_mov_b32_e32 v142, v248
	v_mov_b32_e32 v144, v249
.Lpj_rs_done:
	v_mad_i64_i32 v[208:209], s[28:29], s41, v176, 0
	v_lshl_add_u64 v[208:209], v[208:209], 1, v[214:215]
	v_pk_mul_f32 v[126:127], v[126:127], v[130:131] op_sel_hi:[1,0]
	v_pk_mul_f32 v[128:129], v[128:129], v[130:131] op_sel_hi:[1,0]
	v_pk_mul_f32 v[122:123], v[122:123], v[130:131] op_sel_hi:[1,0]
	v_pk_mul_f32 v[124:125], v[124:125], v[130:131] op_sel_hi:[1,0]
	v_cvt_pk_bf16_f32 v162, v126, v127
	v_cvt_pk_bf16_f32 v163, v128, v129
	v_cvt_pk_bf16_f32 v164, v122, v123
	v_cvt_pk_bf16_f32 v165, v124, v125
	global_store_dwordx4 v[208:209], v[162:165], off
	v_pk_mul_f32 v[118:119], v[118:119], v[130:131] op_sel_hi:[1,0]
	v_pk_mul_f32 v[120:121], v[120:121], v[130:131] op_sel_hi:[1,0]
	v_pk_mul_f32 v[114:115], v[114:115], v[130:131] op_sel_hi:[1,0]
	v_pk_mul_f32 v[116:117], v[116:117], v[130:131] op_sel_hi:[1,0]
	v_cvt_pk_bf16_f32 v148, v118, v119
	v_cvt_pk_bf16_f32 v149, v120, v121
	v_cvt_pk_bf16_f32 v150, v114, v115
	v_cvt_pk_bf16_f32 v151, v116, v117
	global_store_dwordx4 v[208:209], v[148:151], off offset:256
	v_mad_i64_i32 v[208:209], s[28:29], s41, v177, 0
	v_lshl_add_u64 v[208:209], v[208:209], 1, v[214:215]
	v_pk_mul_f32 v[110:111], v[110:111], v[132:133] op_sel_hi:[1,0]
	v_pk_mul_f32 v[112:113], v[112:113], v[132:133] op_sel_hi:[1,0]
	v_pk_mul_f32 v[106:107], v[106:107], v[132:133] op_sel_hi:[1,0]
	v_pk_mul_f32 v[108:109], v[108:109], v[132:133] op_sel_hi:[1,0]
	v_cvt_pk_bf16_f32 v162, v110, v111
	v_cvt_pk_bf16_f32 v163, v112, v113
	v_cvt_pk_bf16_f32 v164, v106, v107
	v_cvt_pk_bf16_f32 v165, v108, v109
	global_store_dwordx4 v[208:209], v[162:165], off
	v_pk_mul_f32 v[102:103], v[102:103], v[132:133] op_sel_hi:[1,0]
	v_pk_mul_f32 v[104:105], v[104:105], v[132:133] op_sel_hi:[1,0]
	v_pk_mul_f32 v[98:99], v[98:99], v[132:133] op_sel_hi:[1,0]
	v_pk_mul_f32 v[100:101], v[100:101], v[132:133] op_sel_hi:[1,0]
	v_cvt_pk_bf16_f32 v148, v102, v103
	v_cvt_pk_bf16_f32 v149, v104, v105
	v_cvt_pk_bf16_f32 v150, v98, v99
	v_cvt_pk_bf16_f32 v151, v100, v101
	global_store_dwordx4 v[208:209], v[148:151], off offset:256
	v_mad_i64_i32 v[208:209], s[28:29], s41, v178, 0
	v_lshl_add_u64 v[208:209], v[208:209], 1, v[214:215]
	v_pk_mul_f32 v[94:95], v[94:95], v[134:135] op_sel_hi:[1,0]
	v_pk_mul_f32 v[96:97], v[96:97], v[134:135] op_sel_hi:[1,0]
	v_pk_mul_f32 v[90:91], v[90:91], v[134:135] op_sel_hi:[1,0]
	v_pk_mul_f32 v[92:93], v[92:93], v[134:135] op_sel_hi:[1,0]
	v_cvt_pk_bf16_f32 v162, v94, v95
	v_cvt_pk_bf16_f32 v163, v96, v97
	v_cvt_pk_bf16_f32 v164, v90, v91
	v_cvt_pk_bf16_f32 v165, v92, v93
	global_store_dwordx4 v[208:209], v[162:165], off
	v_pk_mul_f32 v[86:87], v[86:87], v[134:135] op_sel_hi:[1,0]
	v_pk_mul_f32 v[88:89], v[88:89], v[134:135] op_sel_hi:[1,0]
	v_pk_mul_f32 v[82:83], v[82:83], v[134:135] op_sel_hi:[1,0]
	v_pk_mul_f32 v[84:85], v[84:85], v[134:135] op_sel_hi:[1,0]
	v_cvt_pk_bf16_f32 v148, v86, v87
	v_cvt_pk_bf16_f32 v149, v88, v89
	v_cvt_pk_bf16_f32 v150, v82, v83
	v_cvt_pk_bf16_f32 v151, v84, v85
	global_store_dwordx4 v[208:209], v[148:151], off offset:256
	v_mad_i64_i32 v[208:209], s[28:29], s41, v179, 0
	v_lshl_add_u64 v[208:209], v[208:209], 1, v[214:215]
	v_pk_mul_f32 v[78:79], v[78:79], v[136:137] op_sel_hi:[1,0]
	v_pk_mul_f32 v[80:81], v[80:81], v[136:137] op_sel_hi:[1,0]
	v_pk_mul_f32 v[74:75], v[74:75], v[136:137] op_sel_hi:[1,0]
	v_pk_mul_f32 v[76:77], v[76:77], v[136:137] op_sel_hi:[1,0]
	v_cvt_pk_bf16_f32 v162, v78, v79
	v_cvt_pk_bf16_f32 v163, v80, v81
	v_cvt_pk_bf16_f32 v164, v74, v75
	v_cvt_pk_bf16_f32 v165, v76, v77
	global_store_dwordx4 v[208:209], v[162:165], off
	v_pk_mul_f32 v[70:71], v[70:71], v[136:137] op_sel_hi:[1,0]
	v_pk_mul_f32 v[72:73], v[72:73], v[136:137] op_sel_hi:[1,0]
	v_pk_mul_f32 v[66:67], v[66:67], v[136:137] op_sel_hi:[1,0]
	v_pk_mul_f32 v[68:69], v[68:69], v[136:137] op_sel_hi:[1,0]
	v_cvt_pk_bf16_f32 v148, v70, v71
	v_cvt_pk_bf16_f32 v149, v72, v73
	v_cvt_pk_bf16_f32 v150, v66, v67
	v_cvt_pk_bf16_f32 v151, v68, v69
	global_store_dwordx4 v[208:209], v[148:151], off offset:256
	v_mad_i64_i32 v[208:209], s[28:29], s41, v180, 0
	v_lshl_add_u64 v[208:209], v[208:209], 1, v[214:215]
	v_pk_mul_f32 v[62:63], v[62:63], v[138:139] op_sel_hi:[1,0]
	v_pk_mul_f32 v[64:65], v[64:65], v[138:139] op_sel_hi:[1,0]
	v_pk_mul_f32 v[58:59], v[58:59], v[138:139] op_sel_hi:[1,0]
	v_pk_mul_f32 v[60:61], v[60:61], v[138:139] op_sel_hi:[1,0]
	v_cvt_pk_bf16_f32 v162, v62, v63
	v_cvt_pk_bf16_f32 v163, v64, v65
	v_cvt_pk_bf16_f32 v164, v58, v59
	v_cvt_pk_bf16_f32 v165, v60, v61
	global_store_dwordx4 v[208:209], v[162:165], off
	v_pk_mul_f32 v[54:55], v[54:55], v[138:139] op_sel_hi:[1,0]
	v_pk_mul_f32 v[56:57], v[56:57], v[138:139] op_sel_hi:[1,0]
	v_pk_mul_f32 v[50:51], v[50:51], v[138:139] op_sel_hi:[1,0]
	v_pk_mul_f32 v[52:53], v[52:53], v[138:139] op_sel_hi:[1,0]
	v_cvt_pk_bf16_f32 v148, v54, v55
	v_cvt_pk_bf16_f32 v149, v56, v57
	v_cvt_pk_bf16_f32 v150, v50, v51
	v_cvt_pk_bf16_f32 v151, v52, v53
	global_store_dwordx4 v[208:209], v[148:151], off offset:256
	v_mad_i64_i32 v[208:209], s[28:29], s41, v181, 0
	v_lshl_add_u64 v[208:209], v[208:209], 1, v[214:215]
	v_pk_mul_f32 v[46:47], v[46:47], v[140:141] op_sel_hi:[1,0]
	v_pk_mul_f32 v[48:49], v[48:49], v[140:141] op_sel_hi:[1,0]
	v_pk_mul_f32 v[42:43], v[42:43], v[140:141] op_sel_hi:[1,0]
	v_pk_mul_f32 v[44:45], v[44:45], v[140:141] op_sel_hi:[1,0]
	v_cvt_pk_bf16_f32 v162, v46, v47
	v_cvt_pk_bf16_f32 v163, v48, v49
	v_cvt_pk_bf16_f32 v164, v42, v43
	v_cvt_pk_bf16_f32 v165, v44, v45
	global_store_dwordx4 v[208:209], v[162:165], off
	v_pk_mul_f32 v[38:39], v[38:39], v[140:141] op_sel_hi:[1,0]
	v_pk_mul_f32 v[40:41], v[40:41], v[140:141] op_sel_hi:[1,0]
	v_pk_mul_f32 v[34:35], v[34:35], v[140:141] op_sel_hi:[1,0]
	v_pk_mul_f32 v[36:37], v[36:37], v[140:141] op_sel_hi:[1,0]
	v_cvt_pk_bf16_f32 v148, v38, v39
	v_cvt_pk_bf16_f32 v149, v40, v41
	v_cvt_pk_bf16_f32 v150, v34, v35
	v_cvt_pk_bf16_f32 v151, v36, v37
	global_store_dwordx4 v[208:209], v[148:151], off offset:256
	v_mad_i64_i32 v[208:209], s[28:29], s41, v182, 0
	v_lshl_add_u64 v[208:209], v[208:209], 1, v[214:215]
	v_pk_mul_f32 v[30:31], v[30:31], v[142:143] op_sel_hi:[1,0]
	v_pk_mul_f32 v[32:33], v[32:33], v[142:143] op_sel_hi:[1,0]
	v_pk_mul_f32 v[26:27], v[26:27], v[142:143] op_sel_hi:[1,0]
	v_pk_mul_f32 v[28:29], v[28:29], v[142:143] op_sel_hi:[1,0]
	v_cvt_pk_bf16_f32 v162, v30, v31
	v_cvt_pk_bf16_f32 v163, v32, v33
	v_cvt_pk_bf16_f32 v164, v26, v27
	v_cvt_pk_bf16_f32 v165, v28, v29
	global_store_dwordx4 v[208:209], v[162:165], off
	v_pk_mul_f32 v[22:23], v[22:23], v[142:143] op_sel_hi:[1,0]
	v_pk_mul_f32 v[24:25], v[24:25], v[142:143] op_sel_hi:[1,0]
	v_pk_mul_f32 v[18:19], v[18:19], v[142:143] op_sel_hi:[1,0]
	v_pk_mul_f32 v[20:21], v[20:21], v[142:143] op_sel_hi:[1,0]
	v_cvt_pk_bf16_f32 v148, v22, v23
	v_cvt_pk_bf16_f32 v149, v24, v25
	v_cvt_pk_bf16_f32 v150, v18, v19
	v_cvt_pk_bf16_f32 v151, v20, v21
	global_store_dwordx4 v[208:209], v[148:151], off offset:256
	v_mad_i64_i32 v[208:209], s[28:29], s41, v183, 0
	v_lshl_add_u64 v[208:209], v[208:209], 1, v[214:215]
	v_pk_mul_f32 v[14:15], v[14:15], v[144:145] op_sel_hi:[1,0]
	v_pk_mul_f32 v[16:17], v[16:17], v[144:145] op_sel_hi:[1,0]
	v_pk_mul_f32 v[10:11], v[10:11], v[144:145] op_sel_hi:[1,0]
	v_pk_mul_f32 v[12:13], v[12:13], v[144:145] op_sel_hi:[1,0]
	v_cvt_pk_bf16_f32 v162, v14, v15
	v_cvt_pk_bf16_f32 v163, v16, v17
	v_cvt_pk_bf16_f32 v164, v10, v11
	v_cvt_pk_bf16_f32 v165, v12, v13
	global_store_dwordx4 v[208:209], v[162:165], off
	v_pk_mul_f32 v[6:7], v[6:7], v[144:145] op_sel_hi:[1,0]
	v_pk_mul_f32 v[8:9], v[8:9], v[144:145] op_sel_hi:[1,0]
	v_pk_mul_f32 v[2:3], v[2:3], v[144:145] op_sel_hi:[1,0]
	v_pk_mul_f32 v[4:5], v[4:5], v[144:145] op_sel_hi:[1,0]
	v_cvt_pk_bf16_f32 v148, v6, v7
	v_cvt_pk_bf16_f32 v149, v8, v9
	v_cvt_pk_bf16_f32 v150, v2, v3
	v_cvt_pk_bf16_f32 v151, v4, v5
	global_store_dwordx4 v[208:209], v[148:151], off offset:256
	s_andn2_b64 vcc, exec, s[4:5]
	s_mov_b64 s[4:5], -1
	s_cbranch_vccnz .LBB0_801
	s_branch .Lpj_1085

.Lpj_1085:
	s_andn2_b64 vcc, exec, s[2:3]
	s_cbranch_vccnz .LBB0_800
	s_barrier
	s_branch .LBB0_800
